# v12 + alternating k order inside accumulator pairs so consecutive pairs share the weight-side fragment
# speedup vs baseline: 1.0029x; 1.0029x over previous
; #define PG8_STAGE(bufoff, gbase, voff) do { _Pragma("unroll") for (int _i = 0; _i < 2; ++_i) \
;         __builtin_amdgcn_global_load_lds((const unsigned*)((const char*)(gbase) + (voff)[_i]), (PG8_LAS unsigned*)(lds + (bufoff) + ldsw + _i * 8192), 16, 0, 0); } while (0)
; #define PG8_LDA(dst, b, h) do { _Pragma("unroll") for (int m = 0; m < 4; ++m) _Pragma("unroll") for (int k = 0; k < 2; ++k) dst[m][k] = *(const PG8_LAS bf16x8*)(lds + PG8_SA(b, h) + aoff + m * 2048 + k * 1024); } while (0)
; #define PG8_LDB(dst, b, h) do { _Pragma("unroll") for (int n = 0; n < 2; ++n) _Pragma("unroll") for (int k = 0; k < 2; ++k) dst[n][k] = *(const PG8_LAS bf16x8*)(lds + PG8_SB(b, h) + boff + n * 2048 + k * 1024); } while (0)
; #define PG8_MMA(ai, bj, At, Bt) do { __builtin_amdgcn_s_setprio(1); _Pragma("unroll") for (int m = 0; m < 4; ++m) _Pragma("unroll") for (int n = 0; n < 2; ++n) _Pragma("unroll") for (int k = 0; k < 2; ++k) \
;         acc[ai][bj][m][n] = __builtin_amdgcn_mfma_f32_16x16x32_bf16(Bt[n][k], At[m][k], acc[ai][bj][m][n], 0, 0, 0); __builtin_amdgcn_s_setprio(0); } while (0)
; #define PG8_WAIT_V(n) asm volatile("s_waitcnt vmcnt(" #n ")" ::: "memory")
; #define PG8_WAIT_L(n) asm volatile("s_waitcnt lgkmcnt(" #n ")" ::: "memory")
; #define PG8_BAR __builtin_amdgcn_s_barrier()
; #define PG8_SCHED __builtin_amdgcn_sched_barrier(0)
; template <class Epi, class Sched, bool ALIGN_EPI = false, bool SP2 = false>
; __device__ __forceinline__ void gemm_phase(PG8_LAS unsigned char* lds, const Gemm g, const Sched& S, const Epi& E, const int tid) {
;     ...
;             PG8_LDB(B0, 0, 0); PG8_LDB(B1, 0, 1); PG8_SCHED; PG8_LDA(At, 0, 0); PG8_STAGE(PG8_SA(1, 1), a1 + hstep, voffA);
;             PG8_WAIT_V(8); PG8_WAIT_L(0); PG8_BAR; PG8_MMA(0, 0, At, B0); PG8_MMA(0, 1, At, B1); PG8_BAR; PG8_SCHED;
;             PG8_LDA(At, 0, 1); PG8_STAGE(PG8_SB(0, 0), b2, voffB); PG8_STAGE(PG8_SB(0, 1), b2 + hstep, voffB); PG8_STAGE(PG8_SA(0, 0), a2, voffA);
;             PG8_WAIT_V(8); PG8_WAIT_L(0); PG8_BAR; PG8_MMA(1, 0, At, B0); PG8_MMA(1, 1, At, B1); PG8_BAR; PG8_SCHED;
.LBB0_209:
	s_add_i32 s69, s10, 2
	s_add_u32 s74, s0, 0x80
	s_addc_u32 s11, s1, 0
	s_add_i32 s81, 0, 0x10000
	s_cmp_eq_u32 s39, s10
	s_cselect_b32 s11, s31, s11
	s_cselect_b32 s10, s30, s74
	s_cselect_b32 s77, s35, s13
	s_cselect_b32 s76, s34, s12
	s_add_i32 s74, 0, 0x14000
	v_add_u32_e32 v142, s81, v180
	v_add_u32_e32 v168, s74, v180
	s_waitcnt lgkmcnt(0)
	ds_read_b128 v[130:133], v142
	ds_read_b128 v[134:137], v142 offset:1024
	ds_read_b128 v[138:141], v142 offset:2048
	ds_read_b128 v[142:145], v142 offset:3072
	ds_read_b128 v[164:167], v168
	ds_read_b128 v[184:187], v168 offset:1024
	ds_read_b128 v[188:191], v168 offset:2048
	ds_read_b128 v[200:203], v168 offset:3072
	v_lshl_add_u64 v[168:169], s[0:1], 0, v[160:161]
	s_add_i32 m0, s78, 0xc000
	ds_read_b128 v[204:207], v181
	ds_read_b128 v[208:211], v181 offset:1024
	ds_read_b128 v[212:215], v181 offset:2048
	ds_read_b128 v[216:219], v181 offset:3072
	ds_read_b128 v[220:223], v181 offset:4096
	ds_read_b128 v[226:229], v181 offset:5120
	ds_read_b128 v[238:241], v181 offset:6144
	ds_read_b128 v[242:245], v181 offset:7168
	global_load_lds_dwordx4 v[168:169], off
	v_lshl_add_u64 v[168:169], s[0:1], 0, v[162:163]
	s_add_i32 m0, s78, 0xe000
	s_nop 0
	global_load_lds_dwordx4 v[168:169], off
	s_waitcnt vmcnt(8)
	s_waitcnt lgkmcnt(0)
	s_barrier
	s_setprio 1
	s_waitcnt lgkmcnt(0)
	v_mfma_f32_16x16x32_bf16 v[126:129], v[130:133], v[204:207], v[126:129]
	v_mfma_f32_16x16x32_bf16 v[126:129], v[134:137], v[208:211], v[126:129]
	v_mfma_f32_16x16x32_bf16 v[110:113], v[134:137], v[216:219], v[110:113]
	v_mfma_f32_16x16x32_bf16 v[110:113], v[130:133], v[212:215], v[110:113]
	v_mfma_f32_16x16x32_bf16 v[94:97], v[130:133], v[220:223], v[94:97]
	v_mfma_f32_16x16x32_bf16 v[94:97], v[134:137], v[226:229], v[94:97]
	v_mfma_f32_16x16x32_bf16 v[78:81], v[134:137], v[242:245], v[78:81]
	v_mfma_f32_16x16x32_bf16 v[78:81], v[130:133], v[238:241], v[78:81]
	v_mfma_f32_16x16x32_bf16 v[74:77], v[138:141], v[238:241], v[74:77]
	v_mfma_f32_16x16x32_bf16 v[74:77], v[142:145], v[242:245], v[74:77]
	v_mfma_f32_16x16x32_bf16 v[90:93], v[142:145], v[226:229], v[90:93]
	v_mfma_f32_16x16x32_bf16 v[90:93], v[138:141], v[220:223], v[90:93]
	v_mfma_f32_16x16x32_bf16 v[106:109], v[138:141], v[212:215], v[106:109]
	v_mfma_f32_16x16x32_bf16 v[106:109], v[142:145], v[216:219], v[106:109]
	v_mfma_f32_16x16x32_bf16 v[122:125], v[142:145], v[208:211], v[122:125]
	v_mfma_f32_16x16x32_bf16 v[122:125], v[138:141], v[204:207], v[122:125]
	s_setprio 0
	s_setprio 1
	v_mfma_f32_16x16x32_bf16 v[118:121], v[164:167], v[204:207], v[118:121]
	v_mfma_f32_16x16x32_bf16 v[118:121], v[184:187], v[208:211], v[118:121]
	v_mfma_f32_16x16x32_bf16 v[102:105], v[184:187], v[216:219], v[102:105]
	v_mfma_f32_16x16x32_bf16 v[102:105], v[164:167], v[212:215], v[102:105]
	v_mfma_f32_16x16x32_bf16 v[86:89], v[164:167], v[220:223], v[86:89]
	v_mfma_f32_16x16x32_bf16 v[86:89], v[184:187], v[226:229], v[86:89]
	v_mfma_f32_16x16x32_bf16 v[70:73], v[184:187], v[242:245], v[70:73]
	v_mfma_f32_16x16x32_bf16 v[70:73], v[164:167], v[238:241], v[70:73]
	v_mfma_f32_16x16x32_bf16 v[66:69], v[188:191], v[238:241], v[66:69]
	v_mfma_f32_16x16x32_bf16 v[66:69], v[200:203], v[242:245], v[66:69]
	v_mfma_f32_16x16x32_bf16 v[82:85], v[200:203], v[226:229], v[82:85]
	v_mfma_f32_16x16x32_bf16 v[82:85], v[188:191], v[220:223], v[82:85]
	v_mfma_f32_16x16x32_bf16 v[98:101], v[188:191], v[212:215], v[98:101]
	v_mfma_f32_16x16x32_bf16 v[98:101], v[200:203], v[216:219], v[98:101]
	v_mfma_f32_16x16x32_bf16 v[114:117], v[200:203], v[208:211], v[114:117]
	v_mfma_f32_16x16x32_bf16 v[114:117], v[188:191], v[204:207], v[114:117]
	s_setprio 0
	s_barrier
	s_add_i32 s81, s81, s75
	v_lshl_add_u64 v[168:169], s[76:77], 0, v[148:149]
	s_mov_b32 m0, s81
	ds_read_b128 v[204:207], v181 offset:16384
	ds_read_b128 v[208:211], v181 offset:17408
	ds_read_b128 v[212:215], v181 offset:18432
	ds_read_b128 v[216:219], v181 offset:19456
	ds_read_b128 v[220:223], v181 offset:20480
	ds_read_b128 v[226:229], v181 offset:21504
	ds_read_b128 v[238:241], v181 offset:22528
	ds_read_b128 v[242:245], v181 offset:23552
	global_load_lds_dwordx4 v[168:169], off
	s_add_i32 m0, s81, 0x2000
	v_lshl_add_u64 v[246:247], s[76:77], 0, v[152:153]
	s_add_u32 s76, s76, s82
	s_addc_u32 s77, s77, 0
	s_add_i32 s74, s74, s75
	global_load_lds_dwordx4 v[246:247], off
	v_lshl_add_u64 v[248:249], s[76:77], 0, v[148:149]
	s_mov_b32 m0, s74
	v_lshl_add_u64 v[250:251], s[76:77], 0, v[152:153]
	global_load_lds_dwordx4 v[248:249], off
	s_add_i32 m0, s74, 0x2000
	v_lshl_add_u64 v[252:253], s[10:11], 0, v[146:147]
	global_load_lds_dwordx4 v[250:251], off
	s_mov_b32 m0, s78
	v_lshl_add_u64 v[194:195], s[10:11], 0, v[150:151]
	global_load_lds_dwordx4 v[252:253], off
	s_mov_b32 m0, s79
	s_nop 0
	global_load_lds_dwordx4 v[194:195], off
	s_waitcnt vmcnt(8)
	s_waitcnt lgkmcnt(0)
	s_barrier
; #define PG8_STAGE(bufoff, gbase, voff) do { _Pragma("unroll") for (int _i = 0; _i < 2; ++_i) \
;         __builtin_amdgcn_global_load_lds((const unsigned*)((const char*)(gbase) + (voff)[_i]), (PG8_LAS unsigned*)(lds + (bufoff) + ldsw + _i * 8192), 16, 0, 0); } while (0)
; #define PG8_LDA(dst, b, h) do { _Pragma("unroll") for (int m = 0; m < 4; ++m) _Pragma("unroll") for (int k = 0; k < 2; ++k) dst[m][k] = *(const PG8_LAS bf16x8*)(lds + PG8_SA(b, h) + aoff + m * 2048 + k * 1024); } while (0)
; #define PG8_LDB(dst, b, h) do { _Pragma("unroll") for (int n = 0; n < 2; ++n) _Pragma("unroll") for (int k = 0; k < 2; ++k) dst[n][k] = *(const PG8_LAS bf16x8*)(lds + PG8_SB(b, h) + boff + n * 2048 + k * 1024); } while (0)
; #define PG8_MMA(ai, bj, At, Bt) do { __builtin_amdgcn_s_setprio(1); _Pragma("unroll") for (int m = 0; m < 4; ++m) _Pragma("unroll") for (int n = 0; n < 2; ++n) _Pragma("unroll") for (int k = 0; k < 2; ++k) \
;         acc[ai][bj][m][n] = __builtin_amdgcn_mfma_f32_16x16x32_bf16(Bt[n][k], At[m][k], acc[ai][bj][m][n], 0, 0, 0); __builtin_amdgcn_s_setprio(0); } while (0)
; #define PG8_WAIT_V(n) asm volatile("s_waitcnt vmcnt(" #n ")" ::: "memory")
; #define PG8_WAIT_L(n) asm volatile("s_waitcnt lgkmcnt(" #n ")" ::: "memory")
; #define PG8_BAR __builtin_amdgcn_s_barrier()
; #define PG8_SCHED __builtin_amdgcn_sched_barrier(0)
; template <class Epi, class Sched, bool ALIGN_EPI = false, bool SP2 = false>
; __device__ __forceinline__ void gemm_phase(PG8_LAS unsigned char* lds, const Gemm g, const Sched& S, const Epi& E, const int tid) {
;     ...
;             PG8_WAIT_V(8); PG8_WAIT_L(0); PG8_BAR; PG8_MMA(1, 0, At, B0); PG8_MMA(1, 1, At, B1); PG8_BAR; PG8_SCHED;
;             PG8_LDB(B0, 1, 0); PG8_LDB(B1, 1, 1); PG8_SCHED; PG8_LDA(At, 1, 0); PG8_STAGE(PG8_SA(0, 1), a2 + hstep, voffA);
;             PG8_WAIT_V(8); PG8_WAIT_L(0); PG8_BAR; PG8_MMA(0, 0, At, B0); PG8_MMA(0, 1, At, B1); PG8_BAR; PG8_SCHED;
	s_setprio 1
	s_waitcnt lgkmcnt(0)
	v_mfma_f32_16x16x32_bf16 v[62:65], v[130:133], v[204:207], v[62:65]
	v_mfma_f32_16x16x32_bf16 v[62:65], v[134:137], v[208:211], v[62:65]
	v_mfma_f32_16x16x32_bf16 v[46:49], v[134:137], v[216:219], v[46:49]
	v_mfma_f32_16x16x32_bf16 v[46:49], v[130:133], v[212:215], v[46:49]
	v_mfma_f32_16x16x32_bf16 v[30:33], v[130:133], v[220:223], v[30:33]
	v_mfma_f32_16x16x32_bf16 v[30:33], v[134:137], v[226:229], v[30:33]
	v_mfma_f32_16x16x32_bf16 v[14:17], v[134:137], v[242:245], v[14:17]
	v_mfma_f32_16x16x32_bf16 v[14:17], v[130:133], v[238:241], v[14:17]
	v_mfma_f32_16x16x32_bf16 v[10:13], v[138:141], v[238:241], v[10:13]
	v_mfma_f32_16x16x32_bf16 v[10:13], v[142:145], v[242:245], v[10:13]
	v_mfma_f32_16x16x32_bf16 v[26:29], v[142:145], v[226:229], v[26:29]
	v_mfma_f32_16x16x32_bf16 v[26:29], v[138:141], v[220:223], v[26:29]
	v_mfma_f32_16x16x32_bf16 v[42:45], v[138:141], v[212:215], v[42:45]
	v_mfma_f32_16x16x32_bf16 v[42:45], v[142:145], v[216:219], v[42:45]
	v_mfma_f32_16x16x32_bf16 v[58:61], v[142:145], v[208:211], v[58:61]
	v_mfma_f32_16x16x32_bf16 v[58:61], v[138:141], v[204:207], v[58:61]
	s_setprio 0
	s_setprio 1
	v_mfma_f32_16x16x32_bf16 v[54:57], v[164:167], v[204:207], v[54:57]
	v_mfma_f32_16x16x32_bf16 v[54:57], v[184:187], v[208:211], v[54:57]
	v_mfma_f32_16x16x32_bf16 v[38:41], v[184:187], v[216:219], v[38:41]
	v_mfma_f32_16x16x32_bf16 v[38:41], v[164:167], v[212:215], v[38:41]
	v_mfma_f32_16x16x32_bf16 v[22:25], v[164:167], v[220:223], v[22:25]
	v_mfma_f32_16x16x32_bf16 v[22:25], v[184:187], v[226:229], v[22:25]
	v_mfma_f32_16x16x32_bf16 v[6:9], v[184:187], v[242:245], v[6:9]
	v_mfma_f32_16x16x32_bf16 v[6:9], v[164:167], v[238:241], v[6:9]
	v_mfma_f32_16x16x32_bf16 v[2:5], v[188:191], v[238:241], v[2:5]
	v_mfma_f32_16x16x32_bf16 v[2:5], v[200:203], v[242:245], v[2:5]
	v_mfma_f32_16x16x32_bf16 v[18:21], v[200:203], v[226:229], v[18:21]
	v_mfma_f32_16x16x32_bf16 v[18:21], v[188:191], v[220:223], v[18:21]
	v_mfma_f32_16x16x32_bf16 v[34:37], v[188:191], v[212:215], v[34:37]
	v_mfma_f32_16x16x32_bf16 v[34:37], v[200:203], v[216:219], v[34:37]
	v_mfma_f32_16x16x32_bf16 v[50:53], v[200:203], v[208:211], v[50:53]
	v_mfma_f32_16x16x32_bf16 v[50:53], v[188:191], v[204:207], v[50:53]
	s_setprio 0
	s_barrier
	s_add_i32 s74, 0, 0x18000
	s_add_i32 s76, 0, 0x1c000
	v_add_u32_e32 v142, s74, v180
	v_add_u32_e32 v183, s76, v180
	ds_read_b128 v[130:133], v142
	ds_read_b128 v[134:137], v142 offset:1024
	ds_read_b128 v[138:141], v142 offset:2048
	ds_read_b128 v[142:145], v142 offset:3072
	ds_read_b128 v[164:167], v183
	ds_read_b128 v[184:187], v183 offset:1024
	ds_read_b128 v[188:191], v183 offset:2048
	ds_read_b128 v[200:203], v183 offset:3072
	s_add_u32 s10, s10, s82
	s_addc_u32 s11, s11, 0
	s_mov_b32 m0, s36
	v_lshl_add_u64 v[198:199], s[10:11], 0, v[146:147]
	ds_read_b128 v[204:207], v181 offset:32768
	ds_read_b128 v[208:211], v181 offset:33792
	ds_read_b128 v[212:215], v181 offset:34816
	ds_read_b128 v[216:219], v181 offset:35840
	ds_read_b128 v[220:223], v181 offset:36864
	ds_read_b128 v[226:229], v181 offset:37888
	ds_read_b128 v[238:241], v181 offset:38912
	ds_read_b128 v[242:245], v181 offset:39936
	global_load_lds_dwordx4 v[198:199], off
	v_lshl_add_u64 v[198:199], s[10:11], 0, v[150:151]
	s_mov_b32 m0, s37
	s_nop 0
	global_load_lds_dwordx4 v[198:199], off
	s_waitcnt vmcnt(8)
	s_waitcnt lgkmcnt(0)
	s_barrier
	s_setprio 1
	s_waitcnt lgkmcnt(0)
	v_mfma_f32_16x16x32_bf16 v[126:129], v[130:133], v[204:207], v[126:129]
	v_mfma_f32_16x16x32_bf16 v[126:129], v[134:137], v[208:211], v[126:129]
	v_mfma_f32_16x16x32_bf16 v[110:113], v[134:137], v[216:219], v[110:113]
	v_mfma_f32_16x16x32_bf16 v[110:113], v[130:133], v[212:215], v[110:113]
	v_mfma_f32_16x16x32_bf16 v[94:97], v[130:133], v[220:223], v[94:97]
	v_mfma_f32_16x16x32_bf16 v[94:97], v[134:137], v[226:229], v[94:97]
	v_mfma_f32_16x16x32_bf16 v[78:81], v[134:137], v[242:245], v[78:81]
	v_mfma_f32_16x16x32_bf16 v[78:81], v[130:133], v[238:241], v[78:81]
	v_mfma_f32_16x16x32_bf16 v[74:77], v[138:141], v[238:241], v[74:77]
	v_mfma_f32_16x16x32_bf16 v[74:77], v[142:145], v[242:245], v[74:77]
	v_mfma_f32_16x16x32_bf16 v[90:93], v[142:145], v[226:229], v[90:93]
	v_mfma_f32_16x16x32_bf16 v[90:93], v[138:141], v[220:223], v[90:93]
	v_mfma_f32_16x16x32_bf16 v[106:109], v[138:141], v[212:215], v[106:109]
	v_mfma_f32_16x16x32_bf16 v[106:109], v[142:145], v[216:219], v[106:109]
	v_mfma_f32_16x16x32_bf16 v[122:125], v[142:145], v[208:211], v[122:125]
	v_mfma_f32_16x16x32_bf16 v[122:125], v[138:141], v[204:207], v[122:125]
	s_setprio 0
	s_setprio 1
	v_mfma_f32_16x16x32_bf16 v[118:121], v[164:167], v[204:207], v[118:121]
	v_mfma_f32_16x16x32_bf16 v[118:121], v[184:187], v[208:211], v[118:121]
	v_mfma_f32_16x16x32_bf16 v[102:105], v[184:187], v[216:219], v[102:105]
	v_mfma_f32_16x16x32_bf16 v[102:105], v[164:167], v[212:215], v[102:105]
	v_mfma_f32_16x16x32_bf16 v[86:89], v[164:167], v[220:223], v[86:89]
	v_mfma_f32_16x16x32_bf16 v[86:89], v[184:187], v[226:229], v[86:89]
	v_mfma_f32_16x16x32_bf16 v[70:73], v[184:187], v[242:245], v[70:73]
	v_mfma_f32_16x16x32_bf16 v[70:73], v[164:167], v[238:241], v[70:73]
	v_mfma_f32_16x16x32_bf16 v[66:69], v[188:191], v[238:241], v[66:69]
	v_mfma_f32_16x16x32_bf16 v[66:69], v[200:203], v[242:245], v[66:69]
	v_mfma_f32_16x16x32_bf16 v[82:85], v[200:203], v[226:229], v[82:85]
	v_mfma_f32_16x16x32_bf16 v[82:85], v[188:191], v[220:223], v[82:85]
	v_mfma_f32_16x16x32_bf16 v[98:101], v[188:191], v[212:215], v[98:101]
	v_mfma_f32_16x16x32_bf16 v[98:101], v[200:203], v[216:219], v[98:101]
	v_mfma_f32_16x16x32_bf16 v[114:117], v[200:203], v[208:211], v[114:117]
	v_mfma_f32_16x16x32_bf16 v[114:117], v[188:191], v[204:207], v[114:117]
	s_setprio 0
	s_barrier
; #define PG8_STAGE(bufoff, gbase, voff) do { _Pragma("unroll") for (int _i = 0; _i < 2; ++_i) \
;         __builtin_amdgcn_global_load_lds((const unsigned*)((const char*)(gbase) + (voff)[_i]), (PG8_LAS unsigned*)(lds + (bufoff) + ldsw + _i * 8192), 16, 0, 0); } while (0)
; #define PG8_LDA(dst, b, h) do { _Pragma("unroll") for (int m = 0; m < 4; ++m) _Pragma("unroll") for (int k = 0; k < 2; ++k) dst[m][k] = *(const PG8_LAS bf16x8*)(lds + PG8_SA(b, h) + aoff + m * 2048 + k * 1024); } while (0)
; #define PG8_MMA(ai, bj, At, Bt) do { __builtin_amdgcn_s_setprio(1); _Pragma("unroll") for (int m = 0; m < 4; ++m) _Pragma("unroll") for (int n = 0; n < 2; ++n) _Pragma("unroll") for (int k = 0; k < 2; ++k) \
;         acc[ai][bj][m][n] = __builtin_amdgcn_mfma_f32_16x16x32_bf16(Bt[n][k], At[m][k], acc[ai][bj][m][n], 0, 0, 0); __builtin_amdgcn_s_setprio(0); } while (0)
; #define PG8_WAIT_V(n) asm volatile("s_waitcnt vmcnt(" #n ")" ::: "memory")
; #define PG8_WAIT_L(n) asm volatile("s_waitcnt lgkmcnt(" #n ")" ::: "memory")
; #define PG8_BAR __builtin_amdgcn_s_barrier()
; #define PG8_SCHED __builtin_amdgcn_sched_barrier(0)
; template <class Epi, class Sched, bool ALIGN_EPI = false, bool SP2 = false>
; __device__ __forceinline__ void gemm_phase(PG8_LAS unsigned char* lds, const Gemm g, const Sched& S, const Epi& E, const int tid) {
;     ...
;         for (int t = 0; t < nt; t += 2) {
;             const bool last = (t == nt - 2);
;             const char* a1 = cA + (size_t)(t + 1) * kstep;
;             const char* a2 = last ? nA : cA + (size_t)(t + 2) * kstep; const char* b2 = last ? nB : cB + (size_t)(t + 2) * kstep;
;             const char* a3 = a2 + kstep; const char* b3 = b2 + kstep;
;     ...
;             PG8_LDA(At, 1, 1); PG8_STAGE(PG8_SB(1, 0), b3, voffB); PG8_STAGE(PG8_SB(1, 1), b3 + hstep, voffB); PG8_STAGE(PG8_SA(1, 0), a3, voffA);
;             PG8_WAIT_V(8); PG8_WAIT_L(0); PG8_BAR; PG8_MMA(1, 0, At, B0); PG8_MMA(1, 1, At, B1); PG8_BAR; PG8_SCHED;
;     ...
;         if constexpr (ALIGN_EPI) { if (wr == 0) PG8_BAR; }
;         if constexpr (!Epi::AFTER_DRAIN) { E(acc, cur, wr, wc, fr, fq); S.done(cur); }
	s_add_i32 s10, s74, s75
	v_lshl_add_u64 v[168:169], v[168:169], 0, s[90:91]
	s_mov_b32 m0, s10
	ds_read_b128 v[204:207], v181 offset:49152
	ds_read_b128 v[208:211], v181 offset:50176
	ds_read_b128 v[212:215], v181 offset:51200
	ds_read_b128 v[216:219], v181 offset:52224
	ds_read_b128 v[220:223], v181 offset:53248
	ds_read_b128 v[226:229], v181 offset:54272
	ds_read_b128 v[238:241], v181 offset:55296
	ds_read_b128 v[242:245], v181 offset:56320
	global_load_lds_dwordx4 v[168:169], off
	v_lshl_add_u64 v[168:169], v[246:247], 0, s[90:91]
	s_add_i32 m0, s10, 0x2000
	s_add_i32 s10, s76, s75
	global_load_lds_dwordx4 v[168:169], off
	v_lshl_add_u64 v[168:169], v[248:249], 0, s[90:91]
	s_mov_b32 m0, s10
	s_nop 0
	global_load_lds_dwordx4 v[168:169], off
	v_lshl_add_u64 v[168:169], v[250:251], 0, s[90:91]
	s_add_i32 m0, s10, 0x2000
	s_nop 0
	global_load_lds_dwordx4 v[168:169], off
	v_lshl_add_u64 v[168:169], v[252:253], 0, s[90:91]
	s_mov_b32 m0, s40
	s_nop 0
	global_load_lds_dwordx4 v[168:169], off
	v_lshl_add_u64 v[168:169], v[194:195], 0, s[90:91]
	s_mov_b32 m0, s41
	s_nop 0
	global_load_lds_dwordx4 v[168:169], off
	s_waitcnt vmcnt(8)
	s_waitcnt lgkmcnt(0)
	s_barrier
	s_setprio 1
	s_waitcnt lgkmcnt(0)
	v_mfma_f32_16x16x32_bf16 v[62:65], v[130:133], v[204:207], v[62:65]
	v_mfma_f32_16x16x32_bf16 v[62:65], v[134:137], v[208:211], v[62:65]
	v_mfma_f32_16x16x32_bf16 v[46:49], v[134:137], v[216:219], v[46:49]
	v_mfma_f32_16x16x32_bf16 v[46:49], v[130:133], v[212:215], v[46:49]
	v_mfma_f32_16x16x32_bf16 v[30:33], v[130:133], v[220:223], v[30:33]
	v_mfma_f32_16x16x32_bf16 v[30:33], v[134:137], v[226:229], v[30:33]
	v_mfma_f32_16x16x32_bf16 v[14:17], v[134:137], v[242:245], v[14:17]
	v_mfma_f32_16x16x32_bf16 v[14:17], v[130:133], v[238:241], v[14:17]
	v_mfma_f32_16x16x32_bf16 v[10:13], v[138:141], v[238:241], v[10:13]
	v_mfma_f32_16x16x32_bf16 v[10:13], v[142:145], v[242:245], v[10:13]
	v_mfma_f32_16x16x32_bf16 v[26:29], v[142:145], v[226:229], v[26:29]
	v_mfma_f32_16x16x32_bf16 v[26:29], v[138:141], v[220:223], v[26:29]
	v_mfma_f32_16x16x32_bf16 v[42:45], v[138:141], v[212:215], v[42:45]
	v_mfma_f32_16x16x32_bf16 v[42:45], v[142:145], v[216:219], v[42:45]
	v_mfma_f32_16x16x32_bf16 v[58:61], v[142:145], v[208:211], v[58:61]
	v_mfma_f32_16x16x32_bf16 v[58:61], v[138:141], v[204:207], v[58:61]
	s_setprio 0
	s_setprio 1
	v_mfma_f32_16x16x32_bf16 v[54:57], v[164:167], v[204:207], v[54:57]
	v_mfma_f32_16x16x32_bf16 v[54:57], v[184:187], v[208:211], v[54:57]
	v_mfma_f32_16x16x32_bf16 v[38:41], v[184:187], v[216:219], v[38:41]
	v_mfma_f32_16x16x32_bf16 v[38:41], v[164:167], v[212:215], v[38:41]
	v_mfma_f32_16x16x32_bf16 v[22:25], v[164:167], v[220:223], v[22:25]
	v_mfma_f32_16x16x32_bf16 v[22:25], v[184:187], v[226:229], v[22:25]
	v_mfma_f32_16x16x32_bf16 v[6:9], v[184:187], v[242:245], v[6:9]
	v_mfma_f32_16x16x32_bf16 v[6:9], v[164:167], v[238:241], v[6:9]
	v_mfma_f32_16x16x32_bf16 v[2:5], v[188:191], v[238:241], v[2:5]
	v_mfma_f32_16x16x32_bf16 v[2:5], v[200:203], v[242:245], v[2:5]
	v_mfma_f32_16x16x32_bf16 v[18:21], v[200:203], v[226:229], v[18:21]
	v_mfma_f32_16x16x32_bf16 v[18:21], v[188:191], v[220:223], v[18:21]
	v_mfma_f32_16x16x32_bf16 v[34:37], v[188:191], v[212:215], v[34:37]
	v_mfma_f32_16x16x32_bf16 v[34:37], v[200:203], v[216:219], v[34:37]
	v_mfma_f32_16x16x32_bf16 v[50:53], v[200:203], v[208:211], v[50:53]
	v_mfma_f32_16x16x32_bf16 v[50:53], v[188:191], v[204:207], v[50:53]
	s_setprio 0
	s_barrier
	s_add_u32 s0, s0, 0x100
	s_addc_u32 s1, s1, 0
	s_add_u32 s12, s12, 0x100
	s_addc_u32 s13, s13, 0
	s_cmp_ge_u32 s69, s84
	s_mov_b32 s10, s69
	s_cbranch_scc0 .LBB0_209
	s_and_b64 vcc, exec, s[22:23]
	s_cbranch_vccz .LBB0_213
	s_barrier
	s_cmp_lt_i32 s3, 3
	s_mov_b64 s[0:1], -1
	s_cbranch_scc0 .LBB0_214
